# adds: first K-loop iteration peeled with inline-zero SrcC on each accumulator's first MFMA; per-tile 128-instruction accumulator zeroing removed
# speedup vs baseline: 1.0649x; 1.0061x over previous
; #define PG8_STAGE(bufoff, gbase, voff) do { _Pragma("unroll") for (int _i = 0; _i < 2; ++_i) \
;         __builtin_amdgcn_global_load_lds((const unsigned*)((const char*)(gbase) + (size_t)_i * r64 + (voff)), (PG8_LAS unsigned*)(lds + (bufoff) + ldsw + _i * 8192), 16, 0, 0); } while (0)
; #define PG8_LDA(dst, b, h) do { _Pragma("unroll") for (int m = 0; m < 4; ++m) _Pragma("unroll") for (int k = 0; k < 2; ++k) dst[m][k] = *(const PG8_LAS bf16x8*)(lds + PG8_SA(b, h) + aoff + m * 2048 + k * 1024); } while (0)
; #define PG8_LDB(dst, b, h) do { _Pragma("unroll") for (int n = 0; n < 2; ++n) _Pragma("unroll") for (int k = 0; k < 2; ++k) dst[n][k] = *(const PG8_LAS bf16x8*)(lds + PG8_SB(b, h) + boff + n * 2048 + k * 1024); } while (0)
; #define PG8_MMA(ai, bj, At, Bt) do { __builtin_amdgcn_s_setprio(1); _Pragma("unroll") for (int m = 0; m < 4; ++m) _Pragma("unroll") for (int n = 0; n < 2; ++n) _Pragma("unroll") for (int k = 0; k < 2; ++k) \
;         acc[ai][bj][m][n] = __builtin_amdgcn_mfma_f32_16x16x32_bf16(Bt[n][k], At[m][k], acc[ai][bj][m][n], 0, 0, 0); __builtin_amdgcn_s_setprio(0); } while (0)
; #define PG8_WAIT_V(n) asm volatile("s_waitcnt vmcnt(" #n ")" ::: "memory")
; #define PG8_WAIT_L(n) asm volatile("s_waitcnt lgkmcnt(" #n ")" ::: "memory")
; #define PG8_BAR __builtin_amdgcn_s_barrier()
; #define PG8_SCHED __builtin_amdgcn_sched_barrier(0)
; template <class Epi, class Sched, bool ALIGN_EPI = false, bool SP2 = false>
; __device__ __forceinline__ void gemm_phase(PG8_LAS unsigned char* lds, const Gemm g, const Sched& S, const Epi& E) {
;     ...
;             PG8_LDB(B0, 0, 0); PG8_LDB(B1, 0, 1); PG8_SCHED; PG8_LDA(At, 0, 0); PG8_STAGE(PG8_SA(1, 1), a1 + hstep, voffA);
;             PG8_WAIT_V(8); PG8_WAIT_L(0); PG8_BAR; PG8_MMA(0, 0, At, B0); PG8_MMA(0, 1, At, B1); PG8_BAR; PG8_SCHED;
;             PG8_LDA(At, 0, 1); PG8_STAGE(PG8_SB(0, 0), b2, voffB); PG8_STAGE(PG8_SB(0, 1), b2 + hstep, voffB); PG8_STAGE(PG8_SA(0, 0), a2, voffA);
;             PG8_WAIT_V(8); PG8_WAIT_L(0); PG8_BAR; PG8_MMA(1, 0, At, B0); PG8_MMA(1, 1, At, B1); PG8_BAR; PG8_SCHED;
.LBB0_167:
	v_and_b32_e32 v2, 63, v214
	s_lshl_b32 s12, s45, 14
	s_lshl_b32 s3, s41, 1
	v_lshlrev_b32_e32 v2, 4, v2
	s_add_u32 s12, s12, s3
	s_add_u32 s12, s64, s12
	s_addc_u32 s13, s65, 0
	s_add_i32 m0, s3, 0x21000
	s_nop 0
	global_load_lds_dwordx4 v2, s[12:13]
	global_load_lds_dwordx4 v2, s[12:13] offset:1024
	s_add_u32 s6, s10, 0x80
	s_addc_u32 s7, s11, 0
	s_add_u32 s10, s8, 0x100
	s_addc_u32 s11, s9, 0
	s_mov_b32 s8, 0
	s_add_i32 s12, s8, 2
	s_add_u32 s3, s6, 0x80
	s_addc_u32 s9, s7, 0
	s_add_i32 s13, 0, 0x10000
	s_cmp_eq_u32 s70, s8
	s_cselect_b32 s9, s93, s9
	s_cselect_b32 s8, s92, s3
	s_cselect_b32 s19, s95, s11
	s_cselect_b32 s18, s94, s10
	s_add_i32 s3, 0, 0x14000
	v_add_u32_e32 v14, s13, v242
	v_add_u32_e32 v30, s3, v242
	s_waitcnt lgkmcnt(0)
	ds_read_b128 v[2:5], v14
	ds_read_b128 v[6:9], v14 offset:1024
	ds_read_b128 v[10:13], v14 offset:2048
	ds_read_b128 v[14:17], v14 offset:3072
	ds_read_b128 v[18:21], v30
	ds_read_b128 v[22:25], v30 offset:1024
	ds_read_b128 v[26:29], v30 offset:2048
	ds_read_b128 v[30:33], v30 offset:3072
	v_lshl_add_u64 v[194:195], s[6:7], 0, v[218:219]
	s_add_i32 m0, s90, 0xc000
	ds_read_b128 v[34:37], v243
	ds_read_b128 v[38:41], v243 offset:1024
	ds_read_b128 v[42:45], v243 offset:2048
	ds_read_b128 v[46:49], v243 offset:3072
	ds_read_b128 v[50:53], v243 offset:4096
	ds_read_b128 v[54:57], v243 offset:5120
	ds_read_b128 v[58:61], v243 offset:6144
	ds_read_b128 v[62:65], v243 offset:7168
	global_load_lds_dwordx4 v[194:195], off
	v_lshl_add_u64 v[194:195], s[6:7], 0, v[220:221]
	s_add_i32 m0, s90, 0xe000
	s_nop 0
	global_load_lds_dwordx4 v[194:195], off
	s_waitcnt vmcnt(8)
	s_waitcnt lgkmcnt(0)
	s_barrier
	s_setprio 1
	s_waitcnt lgkmcnt(0)
	v_mfma_f32_16x16x32_bf16 v[190:193], v[2:5], v[34:37], 0
	v_mfma_f32_16x16x32_bf16 v[186:189], v[10:13], v[34:37], 0
	v_mfma_f32_16x16x32_bf16 v[174:177], v[2:5], v[42:45], 0
	v_mfma_f32_16x16x32_bf16 v[170:173], v[10:13], v[42:45], 0
	v_mfma_f32_16x16x32_bf16 v[158:161], v[2:5], v[50:53], 0
	v_mfma_f32_16x16x32_bf16 v[154:157], v[10:13], v[50:53], 0
	v_mfma_f32_16x16x32_bf16 v[142:145], v[2:5], v[58:61], 0
	v_mfma_f32_16x16x32_bf16 v[138:141], v[10:13], v[58:61], 0
	v_mfma_f32_16x16x32_bf16 v[190:193], v[6:9], v[38:41], v[190:193]
	v_mfma_f32_16x16x32_bf16 v[186:189], v[14:17], v[38:41], v[186:189]
	v_mfma_f32_16x16x32_bf16 v[174:177], v[6:9], v[46:49], v[174:177]
	v_mfma_f32_16x16x32_bf16 v[170:173], v[14:17], v[46:49], v[170:173]
	v_mfma_f32_16x16x32_bf16 v[158:161], v[6:9], v[54:57], v[158:161]
	v_mfma_f32_16x16x32_bf16 v[154:157], v[14:17], v[54:57], v[154:157]
	v_mfma_f32_16x16x32_bf16 v[142:145], v[6:9], v[62:65], v[142:145]
	v_mfma_f32_16x16x32_bf16 v[138:141], v[14:17], v[62:65], v[138:141]
	s_setprio 0
	s_setprio 1
	v_mfma_f32_16x16x32_bf16 v[182:185], v[18:21], v[34:37], 0
	v_mfma_f32_16x16x32_bf16 v[34:37], v[26:29], v[34:37], 0
	v_mfma_f32_16x16x32_bf16 v[182:185], v[22:25], v[38:41], v[182:185]
	v_mfma_f32_16x16x32_bf16 v[34:37], v[30:33], v[38:41], v[34:37]
	v_mfma_f32_16x16x32_bf16 v[38:41], v[18:21], v[42:45], 0
	v_mfma_f32_16x16x32_bf16 v[42:45], v[26:29], v[42:45], 0
	v_mfma_f32_16x16x32_bf16 v[38:41], v[22:25], v[46:49], v[38:41]
	v_mfma_f32_16x16x32_bf16 v[42:45], v[30:33], v[46:49], v[42:45]
	v_mfma_f32_16x16x32_bf16 v[46:49], v[18:21], v[50:53], 0
	v_mfma_f32_16x16x32_bf16 v[50:53], v[26:29], v[50:53], 0
	v_mfma_f32_16x16x32_bf16 v[46:49], v[22:25], v[54:57], v[46:49]
	v_mfma_f32_16x16x32_bf16 v[50:53], v[30:33], v[54:57], v[50:53]
	v_mfma_f32_16x16x32_bf16 v[54:57], v[18:21], v[58:61], 0
	v_mfma_f32_16x16x32_bf16 v[58:61], v[26:29], v[58:61], 0
	v_mfma_f32_16x16x32_bf16 v[54:57], v[22:25], v[62:65], v[54:57]
	v_mfma_f32_16x16x32_bf16 v[58:61], v[30:33], v[62:65], v[58:61]
	s_setprio 0
	s_barrier
	s_add_i32 s13, s13, s41
	v_lshl_add_u64 v[228:229], s[18:19], 0, v[0:1]
	s_mov_b32 m0, s13
	ds_read_b128 v[62:65], v243 offset:16384
	ds_read_b128 v[130:133], v243 offset:17408
	ds_read_b128 v[134:137], v243 offset:18432
	ds_read_b128 v[146:149], v243 offset:19456
	ds_read_b128 v[150:153], v243 offset:20480
	ds_read_b128 v[162:165], v243 offset:21504
	ds_read_b128 v[166:169], v243 offset:22528
	ds_read_b128 v[178:181], v243 offset:23552
	global_load_lds_dwordx4 v[228:229], off
	s_add_i32 m0, s13, 0x2000
	s_add_u32 s18, s18, s58
	v_lshl_add_u64 v[230:231], v[228:229], 0, s[56:57]
	s_addc_u32 s19, s19, s59
	s_add_i32 s3, s3, s41
	global_load_lds_dwordx4 v[230:231], off
	v_lshl_add_u64 v[244:245], s[18:19], 0, v[0:1]
	s_mov_b32 m0, s3
	v_lshl_add_u64 v[246:247], v[244:245], 0, s[56:57]
	global_load_lds_dwordx4 v[244:245], off
	s_add_i32 m0, s3, 0x2000
	v_lshl_add_u64 v[248:249], s[8:9], 0, v[216:217]
	global_load_lds_dwordx4 v[246:247], off
	s_mov_b32 m0, s90
	v_lshl_add_u64 v[250:251], v[248:249], 0, s[56:57]
	global_load_lds_dwordx4 v[248:249], off
	s_mov_b32 m0, s91
	s_nop 0
	global_load_lds_dwordx4 v[250:251], off
	s_waitcnt vmcnt(8)
	s_waitcnt lgkmcnt(0)
	s_barrier
; #define PG8_STAGE(bufoff, gbase, voff) do { _Pragma("unroll") for (int _i = 0; _i < 2; ++_i) \
;         __builtin_amdgcn_global_load_lds((const unsigned*)((const char*)(gbase) + (size_t)_i * r64 + (voff)), (PG8_LAS unsigned*)(lds + (bufoff) + ldsw + _i * 8192), 16, 0, 0); } while (0)
; #define PG8_LDA(dst, b, h) do { _Pragma("unroll") for (int m = 0; m < 4; ++m) _Pragma("unroll") for (int k = 0; k < 2; ++k) dst[m][k] = *(const PG8_LAS bf16x8*)(lds + PG8_SA(b, h) + aoff + m * 2048 + k * 1024); } while (0)
; #define PG8_LDB(dst, b, h) do { _Pragma("unroll") for (int n = 0; n < 2; ++n) _Pragma("unroll") for (int k = 0; k < 2; ++k) dst[n][k] = *(const PG8_LAS bf16x8*)(lds + PG8_SB(b, h) + boff + n * 2048 + k * 1024); } while (0)
; #define PG8_MMA(ai, bj, At, Bt) do { __builtin_amdgcn_s_setprio(1); _Pragma("unroll") for (int m = 0; m < 4; ++m) _Pragma("unroll") for (int n = 0; n < 2; ++n) _Pragma("unroll") for (int k = 0; k < 2; ++k) \
;         acc[ai][bj][m][n] = __builtin_amdgcn_mfma_f32_16x16x32_bf16(Bt[n][k], At[m][k], acc[ai][bj][m][n], 0, 0, 0); __builtin_amdgcn_s_setprio(0); } while (0)
; #define PG8_WAIT_V(n) asm volatile("s_waitcnt vmcnt(" #n ")" ::: "memory")
; #define PG8_WAIT_L(n) asm volatile("s_waitcnt lgkmcnt(" #n ")" ::: "memory")
; #define PG8_BAR __builtin_amdgcn_s_barrier()
; #define PG8_SCHED __builtin_amdgcn_sched_barrier(0)
; template <class Epi, class Sched, bool ALIGN_EPI = false, bool SP2 = false>
; __device__ __forceinline__ void gemm_phase(PG8_LAS unsigned char* lds, const Gemm g, const Sched& S, const Epi& E) {
;     ...
;             PG8_WAIT_V(8); PG8_WAIT_L(0); PG8_BAR; PG8_MMA(1, 0, At, B0); PG8_MMA(1, 1, At, B1); PG8_BAR; PG8_SCHED;
;             PG8_LDB(B0, 1, 0); PG8_LDB(B1, 1, 1); PG8_SCHED; PG8_LDA(At, 1, 0); PG8_STAGE(PG8_SA(0, 1), a2 + hstep, voffA);
;             PG8_WAIT_V(8); PG8_WAIT_L(0); PG8_BAR; PG8_MMA(0, 0, At, B0); PG8_MMA(0, 1, At, B1); PG8_BAR; PG8_SCHED;
	s_setprio 1
	s_waitcnt lgkmcnt(0)
	v_mfma_f32_16x16x32_bf16 v[126:129], v[2:5], v[62:65], 0
	v_mfma_f32_16x16x32_bf16 v[122:125], v[10:13], v[62:65], 0
	v_mfma_f32_16x16x32_bf16 v[110:113], v[2:5], v[134:137], 0
	v_mfma_f32_16x16x32_bf16 v[106:109], v[10:13], v[134:137], 0
	v_mfma_f32_16x16x32_bf16 v[94:97], v[2:5], v[150:153], 0
	v_mfma_f32_16x16x32_bf16 v[90:93], v[10:13], v[150:153], 0
	v_mfma_f32_16x16x32_bf16 v[2:5], v[2:5], v[166:169], 0
	v_mfma_f32_16x16x32_bf16 v[126:129], v[6:9], v[130:133], v[126:129]
	v_mfma_f32_16x16x32_bf16 v[122:125], v[14:17], v[130:133], v[122:125]
	v_mfma_f32_16x16x32_bf16 v[110:113], v[6:9], v[146:149], v[110:113]
	v_mfma_f32_16x16x32_bf16 v[106:109], v[14:17], v[146:149], v[106:109]
	v_mfma_f32_16x16x32_bf16 v[94:97], v[6:9], v[162:165], v[94:97]
	v_mfma_f32_16x16x32_bf16 v[90:93], v[14:17], v[162:165], v[90:93]
	v_mfma_f32_16x16x32_bf16 v[2:5], v[6:9], v[178:181], v[2:5]
	v_mfma_f32_16x16x32_bf16 v[6:9], v[10:13], v[166:169], 0
	v_mfma_f32_16x16x32_bf16 v[6:9], v[14:17], v[178:181], v[6:9]
	s_setprio 0
	s_setprio 1
	v_mfma_f32_16x16x32_bf16 v[74:77], v[26:29], v[134:137], 0
	v_mfma_f32_16x16x32_bf16 v[98:101], v[30:33], v[146:149], v[74:77]
	v_mfma_f32_16x16x32_bf16 v[74:77], v[18:21], v[150:153], 0
	v_mfma_f32_16x16x32_bf16 v[10:13], v[18:21], v[62:65], 0
	v_mfma_f32_16x16x32_bf16 v[14:17], v[26:29], v[62:65], 0
	v_mfma_f32_16x16x32_bf16 v[62:65], v[18:21], v[134:137], 0
	v_mfma_f32_16x16x32_bf16 v[86:89], v[22:25], v[162:165], v[74:77]
	v_mfma_f32_16x16x32_bf16 v[74:77], v[26:29], v[150:153], 0
	v_mfma_f32_16x16x32_bf16 v[18:21], v[18:21], v[166:169], 0
	v_mfma_f32_16x16x32_bf16 v[10:13], v[22:25], v[130:133], v[10:13]
	v_mfma_f32_16x16x32_bf16 v[62:65], v[22:25], v[146:149], v[62:65]
	v_mfma_f32_16x16x32_bf16 v[82:85], v[30:33], v[162:165], v[74:77]
	v_mfma_f32_16x16x32_bf16 v[18:21], v[22:25], v[178:181], v[18:21]
	v_mfma_f32_16x16x32_bf16 v[22:25], v[26:29], v[166:169], 0
	v_mfma_f32_16x16x32_bf16 v[14:17], v[30:33], v[130:133], v[14:17]
	v_mfma_f32_16x16x32_bf16 v[22:25], v[30:33], v[178:181], v[22:25]
	s_setprio 0
	s_barrier
	s_add_i32 s3, 0, 0x18000
	s_add_i32 s13, 0, 0x1c000
	v_add_u32_e32 v70, s3, v242
	v_add_u32_e32 v74, s13, v242
	ds_read_b128 v[26:29], v70
	ds_read_b128 v[30:33], v70 offset:1024
	ds_read_b128 v[66:69], v70 offset:2048
	ds_read_b128 v[70:73], v70 offset:3072
	ds_read_b128 v[194:197], v74
	ds_read_b128 v[198:201], v74 offset:1024
	ds_read_b128 v[202:205], v74 offset:2048
	ds_read_b128 v[206:209], v74 offset:3072
	s_add_u32 s8, s8, s58
	s_addc_u32 s9, s9, s59
	s_mov_b32 m0, s36
	v_lshl_add_u64 v[134:135], s[8:9], 0, v[216:217]
	ds_read_b128 v[74:77], v243 offset:32768
	ds_read_b128 v[78:81], v243 offset:33792
	ds_read_b128 v[102:105], v243 offset:34816
	ds_read_b128 v[114:117], v243 offset:35840
	ds_read_b128 v[118:121], v243 offset:36864
	ds_read_b128 v[130:133], v243 offset:37888
	ds_read_b128 v[210:213], v243 offset:38912
	ds_read_b128 v[224:227], v243 offset:39936
	global_load_lds_dwordx4 v[134:135], off
	v_lshl_add_u64 v[134:135], v[134:135], 0, s[56:57]
	s_mov_b32 m0, s62
	s_nop 0
	global_load_lds_dwordx4 v[134:135], off
	s_waitcnt vmcnt(8)
	s_waitcnt lgkmcnt(0)
	s_barrier
	s_setprio 1
	s_waitcnt lgkmcnt(0)
	v_mfma_f32_16x16x32_bf16 v[134:137], v[26:29], v[74:77], v[190:193]
	v_mfma_f32_16x16x32_bf16 v[190:193], v[30:33], v[78:81], v[134:137]
	v_mfma_f32_16x16x32_bf16 v[134:137], v[66:69], v[74:77], v[186:189]
	v_mfma_f32_16x16x32_bf16 v[186:189], v[70:73], v[78:81], v[134:137]
	v_mfma_f32_16x16x32_bf16 v[134:137], v[26:29], v[102:105], v[174:177]
	v_mfma_f32_16x16x32_bf16 v[174:177], v[30:33], v[114:117], v[134:137]
	v_mfma_f32_16x16x32_bf16 v[134:137], v[66:69], v[102:105], v[170:173]
	v_mfma_f32_16x16x32_bf16 v[170:173], v[70:73], v[114:117], v[134:137]
	v_mfma_f32_16x16x32_bf16 v[134:137], v[26:29], v[118:121], v[158:161]
	v_mfma_f32_16x16x32_bf16 v[158:161], v[30:33], v[130:133], v[134:137]
	v_mfma_f32_16x16x32_bf16 v[134:137], v[66:69], v[118:121], v[154:157]
	v_mfma_f32_16x16x32_bf16 v[154:157], v[70:73], v[130:133], v[134:137]
	v_mfma_f32_16x16x32_bf16 v[134:137], v[26:29], v[210:213], v[142:145]
	v_mfma_f32_16x16x32_bf16 v[142:145], v[30:33], v[224:227], v[134:137]
	v_mfma_f32_16x16x32_bf16 v[134:137], v[66:69], v[210:213], v[138:141]
	v_mfma_f32_16x16x32_bf16 v[138:141], v[70:73], v[224:227], v[134:137]
	s_setprio 0
	s_setprio 1
	v_mfma_f32_16x16x32_bf16 v[34:37], v[202:205], v[74:77], v[34:37]
	v_mfma_f32_16x16x32_bf16 v[178:181], v[206:209], v[78:81], v[34:37]
	v_mfma_f32_16x16x32_bf16 v[34:37], v[194:197], v[102:105], v[38:41]
	v_mfma_f32_16x16x32_bf16 v[166:169], v[198:201], v[114:117], v[34:37]
	v_mfma_f32_16x16x32_bf16 v[34:37], v[202:205], v[102:105], v[42:45]
	v_mfma_f32_16x16x32_bf16 v[162:165], v[206:209], v[114:117], v[34:37]
	v_mfma_f32_16x16x32_bf16 v[34:37], v[194:197], v[118:121], v[46:49]
	v_mfma_f32_16x16x32_bf16 v[150:153], v[198:201], v[130:133], v[34:37]
	v_mfma_f32_16x16x32_bf16 v[34:37], v[202:205], v[118:121], v[50:53]
	v_mfma_f32_16x16x32_bf16 v[134:137], v[194:197], v[74:77], v[182:185]
	v_mfma_f32_16x16x32_bf16 v[146:149], v[206:209], v[130:133], v[34:37]
	v_mfma_f32_16x16x32_bf16 v[34:37], v[194:197], v[210:213], v[54:57]
	v_mfma_f32_16x16x32_bf16 v[182:185], v[198:201], v[78:81], v[134:137]
	v_mfma_f32_16x16x32_bf16 v[134:137], v[198:201], v[224:227], v[34:37]
	v_mfma_f32_16x16x32_bf16 v[34:37], v[202:205], v[210:213], v[58:61]
	v_mfma_f32_16x16x32_bf16 v[130:133], v[206:209], v[224:227], v[34:37]
	s_setprio 0
	s_barrier
; #define PG8_STAGE(bufoff, gbase, voff) do { _Pragma("unroll") for (int _i = 0; _i < 2; ++_i) \
;         __builtin_amdgcn_global_load_lds((const unsigned*)((const char*)(gbase) + (size_t)_i * r64 + (voff)), (PG8_LAS unsigned*)(lds + (bufoff) + ldsw + _i * 8192), 16, 0, 0); } while (0)
; #define PG8_LDA(dst, b, h) do { _Pragma("unroll") for (int m = 0; m < 4; ++m) _Pragma("unroll") for (int k = 0; k < 2; ++k) dst[m][k] = *(const PG8_LAS bf16x8*)(lds + PG8_SA(b, h) + aoff + m * 2048 + k * 1024); } while (0)
; #define PG8_MMA(ai, bj, At, Bt) do { __builtin_amdgcn_s_setprio(1); _Pragma("unroll") for (int m = 0; m < 4; ++m) _Pragma("unroll") for (int n = 0; n < 2; ++n) _Pragma("unroll") for (int k = 0; k < 2; ++k) \
;         acc[ai][bj][m][n] = __builtin_amdgcn_mfma_f32_16x16x32_bf16(Bt[n][k], At[m][k], acc[ai][bj][m][n], 0, 0, 0); __builtin_amdgcn_s_setprio(0); } while (0)
; #define PG8_WAIT_V(n) asm volatile("s_waitcnt vmcnt(" #n ")" ::: "memory")
; #define PG8_WAIT_L(n) asm volatile("s_waitcnt lgkmcnt(" #n ")" ::: "memory")
; #define PG8_BAR __builtin_amdgcn_s_barrier()
; #define PG8_SCHED __builtin_amdgcn_sched_barrier(0)
; template <class Epi, class Sched, bool ALIGN_EPI = false, bool SP2 = false>
; __device__ __forceinline__ void gemm_phase(PG8_LAS unsigned char* lds, const Gemm g, const Sched& S, const Epi& E) {
;     ...
;         for (int t = 0; t < nt; t += 2) {
;     ...
;             PG8_LDA(At, 1, 1); PG8_STAGE(PG8_SB(1, 0), b3, voffB); PG8_STAGE(PG8_SB(1, 1), b3 + hstep, voffB); PG8_STAGE(PG8_SA(1, 0), a3, voffA);
;             PG8_WAIT_V(8); PG8_WAIT_L(0); PG8_BAR; PG8_MMA(1, 0, At, B0); PG8_MMA(1, 1, At, B1); PG8_BAR; PG8_SCHED;
	s_add_i32 s3, s3, s41
	v_lshl_add_u64 v[74:75], v[228:229], 0, s[34:35]
	s_mov_b32 m0, s3
	s_nop 1
	ds_read_b128 v[34:37], v243 offset:49152
	ds_read_b128 v[38:41], v243 offset:50176
	ds_read_b128 v[42:45], v243 offset:51200
	ds_read_b128 v[46:49], v243 offset:52224
	ds_read_b128 v[50:53], v243 offset:53248
	ds_read_b128 v[54:57], v243 offset:54272
	ds_read_b128 v[58:61], v243 offset:55296
	ds_read_b128 v[210:213], v243 offset:56320
	global_load_lds_dwordx4 v[74:75], off
	v_lshl_add_u64 v[74:75], v[230:231], 0, s[34:35]
	s_add_i32 m0, s3, 0x2000
	s_add_i32 s3, s13, s41
	global_load_lds_dwordx4 v[74:75], off
	v_lshl_add_u64 v[74:75], v[244:245], 0, s[34:35]
	s_mov_b32 m0, s3
	s_nop 0
	global_load_lds_dwordx4 v[74:75], off
	v_lshl_add_u64 v[74:75], v[246:247], 0, s[34:35]
	s_add_i32 m0, s3, 0x2000
	s_nop 0
	global_load_lds_dwordx4 v[74:75], off
	v_lshl_add_u64 v[74:75], v[248:249], 0, s[34:35]
	s_mov_b32 m0, s81
	s_nop 0
	global_load_lds_dwordx4 v[74:75], off
	v_lshl_add_u64 v[74:75], v[250:251], 0, s[34:35]
	s_mov_b32 m0, s1
	s_nop 0
	global_load_lds_dwordx4 v[74:75], off
	s_waitcnt vmcnt(8)
	s_waitcnt lgkmcnt(0)
	s_barrier
	s_setprio 1
	s_waitcnt lgkmcnt(0)
	v_mfma_f32_16x16x32_bf16 v[74:77], v[26:29], v[34:37], v[126:129]
	v_mfma_f32_16x16x32_bf16 v[126:129], v[30:33], v[38:41], v[74:77]
	v_mfma_f32_16x16x32_bf16 v[74:77], v[66:69], v[34:37], v[122:125]
	v_mfma_f32_16x16x32_bf16 v[122:125], v[70:73], v[38:41], v[74:77]
	v_mfma_f32_16x16x32_bf16 v[74:77], v[26:29], v[42:45], v[110:113]
	v_mfma_f32_16x16x32_bf16 v[110:113], v[30:33], v[46:49], v[74:77]
	v_mfma_f32_16x16x32_bf16 v[74:77], v[66:69], v[42:45], v[106:109]
	v_mfma_f32_16x16x32_bf16 v[106:109], v[70:73], v[46:49], v[74:77]
	v_mfma_f32_16x16x32_bf16 v[74:77], v[26:29], v[50:53], v[94:97]
	v_mfma_f32_16x16x32_bf16 v[2:5], v[26:29], v[58:61], v[2:5]
	v_mfma_f32_16x16x32_bf16 v[94:97], v[30:33], v[54:57], v[74:77]
	v_mfma_f32_16x16x32_bf16 v[74:77], v[66:69], v[50:53], v[90:93]
	v_mfma_f32_16x16x32_bf16 v[78:81], v[30:33], v[210:213], v[2:5]
	v_mfma_f32_16x16x32_bf16 v[2:5], v[66:69], v[58:61], v[6:9]
	v_mfma_f32_16x16x32_bf16 v[90:93], v[70:73], v[54:57], v[74:77]
	v_mfma_f32_16x16x32_bf16 v[74:77], v[70:73], v[210:213], v[2:5]
	s_setprio 0
	s_setprio 1
	v_mfma_f32_16x16x32_bf16 v[2:5], v[194:197], v[34:37], v[10:13]
	v_mfma_f32_16x16x32_bf16 v[118:121], v[198:201], v[38:41], v[2:5]
	v_mfma_f32_16x16x32_bf16 v[2:5], v[202:205], v[34:37], v[14:17]
	v_mfma_f32_16x16x32_bf16 v[114:117], v[206:209], v[38:41], v[2:5]
	v_mfma_f32_16x16x32_bf16 v[2:5], v[194:197], v[42:45], v[62:65]
	v_mfma_f32_16x16x32_bf16 v[102:105], v[198:201], v[46:49], v[2:5]
	v_mfma_f32_16x16x32_bf16 v[2:5], v[202:205], v[42:45], v[98:101]
	v_mfma_f32_16x16x32_bf16 v[98:101], v[206:209], v[46:49], v[2:5]
	v_mfma_f32_16x16x32_bf16 v[2:5], v[194:197], v[50:53], v[86:89]
	v_mfma_f32_16x16x32_bf16 v[86:89], v[198:201], v[54:57], v[2:5]
	v_mfma_f32_16x16x32_bf16 v[2:5], v[202:205], v[50:53], v[82:85]
	v_mfma_f32_16x16x32_bf16 v[82:85], v[206:209], v[54:57], v[2:5]
	v_mfma_f32_16x16x32_bf16 v[2:5], v[194:197], v[58:61], v[18:21]
	v_mfma_f32_16x16x32_bf16 v[70:73], v[198:201], v[210:213], v[2:5]
	v_mfma_f32_16x16x32_bf16 v[2:5], v[202:205], v[58:61], v[22:25]
	v_mfma_f32_16x16x32_bf16 v[66:69], v[206:209], v[210:213], v[2:5]
	s_setprio 0
	s_barrier
	s_add_u32 s6, s6, 0x100
	s_addc_u32 s7, s7, 0
	s_add_u32 s10, s10, 0x100
	s_addc_u32 s11, s11, 0
	s_cmp_ge_u32 s12, s2
	s_mov_b32 s8, s12
	s_cbranch_scc1 .Lkloop_done

; #define PG8_BAR __builtin_amdgcn_s_barrier()
; template <class Epi, class Sched, bool ALIGN_EPI = false, bool SP2 = false>
; __device__ __forceinline__ void gemm_phase(PG8_LAS unsigned char* lds, const Gemm g, const Sched& S, const Epi& E) {
;     ...
;         if constexpr (ALIGN_EPI) { if (wr == 0) PG8_BAR; }
.Lkloop_done:
	v_readlane_b32 s6, v255, 34
	v_readlane_b32 s7, v255, 35
	s_and_b64 vcc, exec, s[6:7]
	s_cbranch_vccz .LBB0_171
	s_barrier
